# attention: static s_setprio 1 for waves 4-7 (younger half) in place of the s_sleep stagger
# speedup vs baseline: 1.0030x; 1.0030x over previous
.LBB0_955:
	s_waitcnt lgkmcnt(0)
	s_barrier
	v_readlane_b32 s100, v255, 8
	s_cmp_lt_u32 s100, 4
	s_cbranch_scc1 .Lpf_nostag
	s_setprio 1
